# P6 selected-attn loop: row selection mask applied once to row max and exp offset instead of 32 per-score selects; canonicalising max pairs removed (37 fewer VALU per half-step)
# speedup vs baseline: 1.0171x; 1.0171x over previous
; __device__ __forceinline__ void partialSM(f32x16& p0, f32x16& p1, float& m_reg, float& mn, float& alpha) {
;     float pmax = p0[0];
; #pragma unroll
;     for (int r = 1; r < 16; ++r) pmax = fmaxf(pmax, p0[r]);
; #pragma unroll
;     for (int r = 0; r < 16; ++r) pmax = fmaxf(pmax, p1[r]);
;     { auto rr = __builtin_amdgcn_permlane32_swap(__float_as_uint(pmax), __float_as_uint(pmax), false, false);
;       pmax = fmaxf(__uint_as_float(rr[0]), __uint_as_float(rr[1])); }
;     constexpr float C2 = 1.4426950408889634f * SM_SCALE;
;     if (__builtin_expect(__all((pmax - m_reg) * SM_SCALE <= THR), 1)) { mn = m_reg; alpha = 1.f; }
;     else { mn = fmaxf(m_reg, pmax); alpha = __builtin_amdgcn_exp2f((m_reg - mn) * C2); m_reg = mn; }
;     const float mnL = -mn * C2;
; #pragma unroll
;     for (int r = 0; r < 16; ++r) p0[r] = fmaf(p0[r], C2, mnL);
; #pragma unroll
;     for (int r = 0; r < 16; ++r) p1[r] = fmaf(p1[r], C2, mnL);
; #pragma unroll
;     for (int r = 0; r < 16; ++r) p0[r] = __builtin_amdgcn_exp2f(p0[r]);
; }
.LBB0_1373:
	v_cmp_eq_u32_e64 s[6:7], 0, v0
	v_max_f32_e32 v0, v112, v113
	v_max3_f32 v0, v0, v114, v115
	v_max3_f32 v0, v0, v116, v117
	v_max3_f32 v0, v0, v118, v119
	v_max3_f32 v0, v0, v120, v121
	v_max3_f32 v0, v0, v122, v123
	v_max3_f32 v0, v0, v124, v125
	v_max3_f32 v0, v0, v126, v127
	v_max3_f32 v0, v0, v80, v81
	v_max3_f32 v0, v0, v82, v83
	v_max3_f32 v0, v0, v84, v85
	v_max3_f32 v0, v0, v86, v87
	v_max3_f32 v0, v0, v88, v89
	v_max3_f32 v0, v0, v90, v91
	v_max3_f32 v0, v0, v92, v93
	v_max3_f32 v0, v0, v94, v95
	v_cndmask_b32_e64 v0, v0, v216, s[6:7]
	v_mov_b32_e32 v14, v0
	s_nop 1
	v_permlane32_swap_b32_e32 v0, v14
	v_max_f32_e32 v0, v0, v14
	v_sub_f32_e32 v14, v0, v228
	v_mul_f32_e32 v14, 0x3db504f3, v14
	v_cmp_ge_f32_e32 vcc, s93, v14
	v_max_f32_e32 v0, v228, v0
	v_sub_f32_e32 v14, v228, v0
	v_mul_f32_e32 v14, 0x3e0293ee, v14
	s_cmp_eq_u64 vcc, exec
	v_exp_f32_e32 v14, v14
	s_cselect_b64 vcc, -1, 0
	v_cndmask_b32_e32 v228, v0, v228, vcc
	v_mul_f32_e32 v0, 0xbe0293ee, v228
	v_cndmask_b32_e64 v14, v14, 1.0, vcc
	v_cndmask_b32_e64 v0, v0, v216, s[6:7]
	v_fmamk_f32 v112, v112, 0x3e0293ee, v0
	v_fmamk_f32 v113, v113, 0x3e0293ee, v0
	v_fmamk_f32 v114, v114, 0x3e0293ee, v0
	v_fmamk_f32 v115, v115, 0x3e0293ee, v0
	v_fmamk_f32 v116, v116, 0x3e0293ee, v0
	v_fmamk_f32 v117, v117, 0x3e0293ee, v0
	v_fmamk_f32 v118, v118, 0x3e0293ee, v0
	v_fmamk_f32 v119, v119, 0x3e0293ee, v0
	v_fmamk_f32 v120, v120, 0x3e0293ee, v0
	v_fmamk_f32 v121, v121, 0x3e0293ee, v0
	v_fmamk_f32 v122, v122, 0x3e0293ee, v0
	v_fmamk_f32 v123, v123, 0x3e0293ee, v0
	v_fmamk_f32 v124, v124, 0x3e0293ee, v0
	v_fmamk_f32 v125, v125, 0x3e0293ee, v0
	v_fmamk_f32 v126, v126, 0x3e0293ee, v0
	v_fmamk_f32 v127, v127, 0x3e0293ee, v0
	v_exp_f32_e32 v112, v112
	v_exp_f32_e32 v113, v113
	v_exp_f32_e32 v114, v114
	v_exp_f32_e32 v115, v115
	v_exp_f32_e32 v116, v116
	v_exp_f32_e32 v117, v117
	v_exp_f32_e32 v118, v118
	v_exp_f32_e32 v119, v119
	v_exp_f32_e32 v120, v120
	v_exp_f32_e32 v121, v121
	v_exp_f32_e32 v122, v122
	v_exp_f32_e32 v123, v123
	v_exp_f32_e32 v124, v124
	v_exp_f32_e32 v125, v125
	v_exp_f32_e32 v126, v126
	v_exp_f32_e32 v127, v127
	v_pk_fma_f32 v[94:95], v[94:95], s[72:73], v[0:1] op_sel_hi:[1,0,0]
	v_pk_fma_f32 v[92:93], v[92:93], s[72:73], v[0:1] op_sel_hi:[1,0,0]
	v_pk_fma_f32 v[90:91], v[90:91], s[72:73], v[0:1] op_sel_hi:[1,0,0]
	v_pk_fma_f32 v[88:89], v[88:89], s[72:73], v[0:1] op_sel_hi:[1,0,0]
	v_pk_fma_f32 v[86:87], v[86:87], s[72:73], v[0:1] op_sel_hi:[1,0,0]
	v_pk_fma_f32 v[84:85], v[84:85], s[72:73], v[0:1] op_sel_hi:[1,0,0]
	v_pk_fma_f32 v[82:83], v[82:83], s[72:73], v[0:1] op_sel_hi:[1,0,0]
	v_pk_fma_f32 v[80:81], v[80:81], s[72:73], v[0:1] op_sel_hi:[1,0,0]

; __device__ __forceinline__ void partialSM(f32x16& p0, f32x16& p1, float& m_reg, float& mn, float& alpha) {
;     float pmax = p0[0];
; #pragma unroll
;     for (int r = 1; r < 16; ++r) pmax = fmaxf(pmax, p0[r]);
; #pragma unroll
;     for (int r = 0; r < 16; ++r) pmax = fmaxf(pmax, p1[r]);
;     { auto rr = __builtin_amdgcn_permlane32_swap(__float_as_uint(pmax), __float_as_uint(pmax), false, false);
;       pmax = fmaxf(__uint_as_float(rr[0]), __uint_as_float(rr[1])); }
;     constexpr float C2 = 1.4426950408889634f * SM_SCALE;
;     if (__builtin_expect(__all((pmax - m_reg) * SM_SCALE <= THR), 1)) { mn = m_reg; alpha = 1.f; }
;     else { mn = fmaxf(m_reg, pmax); alpha = __builtin_amdgcn_exp2f((m_reg - mn) * C2); m_reg = mn; }
;     const float mnL = -mn * C2;
; #pragma unroll
;     for (int r = 0; r < 16; ++r) p0[r] = fmaf(p0[r], C2, mnL);
; #pragma unroll
;     for (int r = 0; r < 16; ++r) p1[r] = fmaf(p1[r], C2, mnL);
; #pragma unroll
;     for (int r = 0; r < 16; ++r) p0[r] = __builtin_amdgcn_exp2f(p0[r]);
; }
.LBB0_1425:
	v_cmp_eq_u32_e64 s[4:5], 0, v0
	v_max_f32_e32 v0, v128, v129
	v_max3_f32 v0, v0, v130, v131
	v_max3_f32 v0, v0, v132, v133
	v_max3_f32 v0, v0, v134, v135
	v_max3_f32 v0, v0, v136, v137
	v_max3_f32 v0, v0, v138, v139
	v_max3_f32 v0, v0, v140, v141
	v_max3_f32 v0, v0, v142, v143
	v_max3_f32 v0, v0, v96, v97
	v_max3_f32 v0, v0, v98, v99
	v_max3_f32 v0, v0, v100, v101
	v_max3_f32 v0, v0, v102, v103
	v_max3_f32 v0, v0, v104, v105
	v_max3_f32 v0, v0, v106, v107
	v_max3_f32 v0, v0, v108, v109
	v_max3_f32 v0, v0, v110, v111
	v_cndmask_b32_e64 v0, v0, v216, s[4:5]
	v_mov_b32_e32 v14, v0
	s_nop 1
	v_permlane32_swap_b32_e32 v0, v14
	v_max_f32_e32 v0, v0, v14
	v_sub_f32_e32 v14, v0, v228
	v_mul_f32_e32 v14, 0x3db504f3, v14
	v_cmp_ge_f32_e32 vcc, s93, v14
	v_max_f32_e32 v0, v228, v0
	v_sub_f32_e32 v14, v228, v0
	v_mul_f32_e32 v14, 0x3e0293ee, v14
	s_cmp_eq_u64 vcc, exec
	v_exp_f32_e32 v14, v14
	s_cselect_b64 vcc, -1, 0
	v_cndmask_b32_e32 v228, v0, v228, vcc
	v_mul_f32_e32 v0, 0xbe0293ee, v228
	v_cndmask_b32_e64 v243, v14, 1.0, vcc
	v_cndmask_b32_e64 v0, v0, v216, s[4:5]
	v_fmamk_f32 v128, v128, 0x3e0293ee, v0
	v_fmamk_f32 v129, v129, 0x3e0293ee, v0
	v_fmamk_f32 v130, v130, 0x3e0293ee, v0
	v_fmamk_f32 v131, v131, 0x3e0293ee, v0
	v_fmamk_f32 v132, v132, 0x3e0293ee, v0
	v_fmamk_f32 v133, v133, 0x3e0293ee, v0
	v_fmamk_f32 v134, v134, 0x3e0293ee, v0
	v_fmamk_f32 v135, v135, 0x3e0293ee, v0
	v_fmamk_f32 v136, v136, 0x3e0293ee, v0
	v_fmamk_f32 v137, v137, 0x3e0293ee, v0
	v_fmamk_f32 v138, v138, 0x3e0293ee, v0
	v_fmamk_f32 v139, v139, 0x3e0293ee, v0
	v_fmamk_f32 v140, v140, 0x3e0293ee, v0
	v_fmamk_f32 v141, v141, 0x3e0293ee, v0
	v_fmamk_f32 v142, v142, 0x3e0293ee, v0
	v_fmamk_f32 v143, v143, 0x3e0293ee, v0
	v_exp_f32_e32 v128, v128
	v_exp_f32_e32 v129, v129
	v_exp_f32_e32 v130, v130
	v_exp_f32_e32 v131, v131
	v_exp_f32_e32 v132, v132
	v_exp_f32_e32 v133, v133
	v_exp_f32_e32 v134, v134
	v_exp_f32_e32 v135, v135
	v_exp_f32_e32 v136, v136
	v_exp_f32_e32 v137, v137
	v_exp_f32_e32 v138, v138
	v_exp_f32_e32 v139, v139
	v_exp_f32_e32 v140, v140
	v_exp_f32_e32 v141, v141
	v_exp_f32_e32 v142, v142
	v_exp_f32_e32 v143, v143
	v_pk_fma_f32 v[110:111], v[110:111], s[72:73], v[0:1] op_sel_hi:[1,0,0]
	v_pk_fma_f32 v[108:109], v[108:109], s[72:73], v[0:1] op_sel_hi:[1,0,0]
	v_pk_fma_f32 v[106:107], v[106:107], s[72:73], v[0:1] op_sel_hi:[1,0,0]
	v_pk_fma_f32 v[104:105], v[104:105], s[72:73], v[0:1] op_sel_hi:[1,0,0]
	v_pk_fma_f32 v[102:103], v[102:103], s[72:73], v[0:1] op_sel_hi:[1,0,0]
	v_pk_fma_f32 v[100:101], v[100:101], s[72:73], v[0:1] op_sel_hi:[1,0,0]
	v_pk_fma_f32 v[98:99], v[98:99], s[72:73], v[0:1] op_sel_hi:[1,0,0]
	v_pk_fma_f32 v[96:97], v[96:97], s[72:73], v[0:1] op_sel_hi:[1,0,0]
